# GEMM K-loops: removed the adjacent s_setprio 0 / s_setprio 1 pair sitting between MFMA 16 and 17 of every 32-MFMA segment (inserted issue slots in an MFMA-paced segment, sec 6.1(2))
# baseline (speedup 1.0000x reference)
; #define PG8_STAGE(bufoff, gbase, voff) do { _Pragma("unroll") for (int _i = 0; _i < 2; ++_i) \
;         __builtin_amdgcn_global_load_lds((const unsigned*)((const char*)(gbase) + (voff)[_i]), (LAS unsigned*)(lds + (bufoff) + ldsw + _i * 8192), 16, 0, 0); } while (0)
; #define PG8_LDA(dst, b, h) do { _Pragma("unroll") for (int m = 0; m < 4; ++m) _Pragma("unroll") for (int k = 0; k < 2; ++k) dst[m][k] = *(const LAS bf16x8*)(lds + PG8_SA(b, h) + aoff + m * 2048 + k * 1024); } while (0)
; #define PG8_LDB(dst, b, h) do { _Pragma("unroll") for (int n = 0; n < 2; ++n) _Pragma("unroll") for (int k = 0; k < 2; ++k) dst[n][k] = *(const LAS bf16x8*)(lds + PG8_SB(b, h) + boff + n * 2048 + k * 1024); } while (0)
; #define PG8_MMA(ai, bj, At, Bt) do { __builtin_amdgcn_s_setprio(1); _Pragma("unroll") for (int m = 0; m < 4; ++m) _Pragma("unroll") for (int n = 0; n < 2; ++n) _Pragma("unroll") for (int k = 0; k < 2; ++k) \
;         acc[ai][bj][m][n] = __builtin_amdgcn_mfma_f32_16x16x32_bf16(Bt[n][k], At[m][k], acc[ai][bj][m][n], 0, 0, 0); __builtin_amdgcn_s_setprio(0); } while (0)
; #define PG8_WAIT_V(n) asm volatile("s_waitcnt vmcnt(" #n ")" ::: "memory")
; #define PG8_WAIT_L(n) asm volatile("s_waitcnt lgkmcnt(" #n ")" ::: "memory")
; #define PG8_BAR __builtin_amdgcn_s_barrier()
; #define PG8_SCHED __builtin_amdgcn_sched_barrier(0)
; template <class Epi, class Sched, bool ALIGN_EPI = false, bool SP2 = false>
; __device__ __forceinline__ void gemm_phase(LAS unsigned char* lds, const Gemm g, const Sched& S, const Epi& E) {
;     ...
;             PG8_LDB(B0, 0, 0); PG8_LDB(B1, 0, 1); PG8_SCHED; PG8_LDA(At, 0, 0); PG8_STAGE(PG8_SA(1, 1), a1 + hstep, voffA);
;             PG8_WAIT_V(8); PG8_WAIT_L(0); PG8_BAR; PG8_MMA(0, 0, At, B0); PG8_MMA(0, 1, At, B1); PG8_BAR; PG8_SCHED;
;             PG8_LDA(At, 0, 1); PG8_STAGE(PG8_SB(0, 0), b2, voffB); PG8_STAGE(PG8_SB(0, 1), b2 + hstep, voffB); PG8_STAGE(PG8_SA(0, 0), a2, voffA);
;             PG8_WAIT_V(8); PG8_WAIT_L(0); PG8_BAR; PG8_MMA(1, 0, At, B0); PG8_MMA(1, 1, At, B1); PG8_BAR; PG8_SCHED;
.LBB0_56:
	s_add_u32 s48, s40, 0xfff80080
	s_addc_u32 s49, s41, -1
	s_add_i32 s96, 0, 0x10000
	s_cmp_eq_u32 s54, 28
	s_cselect_b32 s51, s1, s49
	s_cselect_b32 s50, s29, s48
	s_cselect_b32 s49, s11, s62
	s_cselect_b32 s48, vcc_lo, vcc_hi
	s_add_i32 s75, 0, 0x14000
	v_add_u32_e32 v152, s96, v168
	v_add_u32_e32 v164, s75, v168
	ds_read_b128 v[140:143], v152
	ds_read_b128 v[144:147], v152 offset:1024
	ds_read_b128 v[148:151], v152 offset:2048
	ds_read_b128 v[152:155], v152 offset:3072
	ds_read_b128 v[156:159], v164
	ds_read_b128 v[160:163], v164 offset:1024
	ds_read_b128 v[170:173], v164 offset:2048
	ds_read_b128 v[174:177], v164 offset:3072
	v_lshl_add_u64 v[164:165], s[40:41], 0, v[138:139]
	s_add_i32 m0, s74, 0xc000
	ds_read_b128 v[186:189], v169
	ds_read_b128 v[190:193], v169 offset:1024
	ds_read_b128 v[194:197], v169 offset:2048
	ds_read_b128 v[198:201], v169 offset:3072
	ds_read_b128 v[202:205], v169 offset:4096
	ds_read_b128 v[222:225], v169 offset:5120
	ds_read_b128 v[226:229], v169 offset:6144
	ds_read_b128 v[230:233], v169 offset:7168
	global_load_lds_dwordx4 v[164:165], off
	v_lshl_add_u64 v[164:165], s[40:41], 0, v[136:137]
	s_add_i32 m0, s74, 0xe000
	s_nop 0
	global_load_lds_dwordx4 v[164:165], off
	s_waitcnt vmcnt(8)
	s_waitcnt lgkmcnt(0)
	s_barrier
	s_setprio 1
	s_waitcnt lgkmcnt(0)
	v_mfma_f32_16x16x32_bf16 v[122:125], v[140:143], v[186:189], v[122:125]
	v_mfma_f32_16x16x32_bf16 v[114:117], v[148:151], v[186:189], v[114:117]
	v_mfma_f32_16x16x32_bf16 v[102:105], v[140:143], v[194:197], v[102:105]
	v_mfma_f32_16x16x32_bf16 v[98:101], v[148:151], v[194:197], v[98:101]
	v_mfma_f32_16x16x32_bf16 v[94:97], v[140:143], v[202:205], v[94:97]
	v_mfma_f32_16x16x32_bf16 v[78:81], v[148:151], v[202:205], v[78:81]
	v_mfma_f32_16x16x32_bf16 v[126:129], v[140:143], v[226:229], v[126:129]
	v_mfma_f32_16x16x32_bf16 v[118:121], v[148:151], v[226:229], v[118:121]
	v_mfma_f32_16x16x32_bf16 v[122:125], v[144:147], v[190:193], v[122:125]
	v_mfma_f32_16x16x32_bf16 v[114:117], v[152:155], v[190:193], v[114:117]
	v_mfma_f32_16x16x32_bf16 v[102:105], v[144:147], v[198:201], v[102:105]
	v_mfma_f32_16x16x32_bf16 v[98:101], v[152:155], v[198:201], v[98:101]
	v_mfma_f32_16x16x32_bf16 v[94:97], v[144:147], v[222:225], v[94:97]
	v_mfma_f32_16x16x32_bf16 v[78:81], v[152:155], v[222:225], v[78:81]
	v_mfma_f32_16x16x32_bf16 v[126:129], v[144:147], v[230:233], v[126:129]
	v_mfma_f32_16x16x32_bf16 v[118:121], v[152:155], v[230:233], v[118:121]
	v_mfma_f32_16x16x32_bf16 v[106:109], v[156:159], v[186:189], v[106:109]
	v_mfma_f32_16x16x32_bf16 v[86:89], v[170:173], v[186:189], v[86:89]
	v_mfma_f32_16x16x32_bf16 v[82:85], v[156:159], v[194:197], v[82:85]
	v_mfma_f32_16x16x32_bf16 v[74:77], v[170:173], v[194:197], v[74:77]
	v_mfma_f32_16x16x32_bf16 v[70:73], v[156:159], v[202:205], v[70:73]
	v_mfma_f32_16x16x32_bf16 v[66:69], v[170:173], v[202:205], v[66:69]
	v_mfma_f32_16x16x32_bf16 v[110:113], v[156:159], v[226:229], v[110:113]
	v_mfma_f32_16x16x32_bf16 v[90:93], v[170:173], v[226:229], v[90:93]
	v_mfma_f32_16x16x32_bf16 v[106:109], v[160:163], v[190:193], v[106:109]
	v_mfma_f32_16x16x32_bf16 v[86:89], v[174:177], v[190:193], v[86:89]
	v_mfma_f32_16x16x32_bf16 v[82:85], v[160:163], v[198:201], v[82:85]
	v_mfma_f32_16x16x32_bf16 v[74:77], v[174:177], v[198:201], v[74:77]
	v_mfma_f32_16x16x32_bf16 v[70:73], v[160:163], v[222:225], v[70:73]
	v_mfma_f32_16x16x32_bf16 v[66:69], v[174:177], v[222:225], v[66:69]
	v_mfma_f32_16x16x32_bf16 v[110:113], v[160:163], v[230:233], v[110:113]
	v_mfma_f32_16x16x32_bf16 v[90:93], v[174:177], v[230:233], v[90:93]
	s_setprio 0
	s_barrier
	s_add_i32 s96, s96, s69
	v_lshl_add_u64 v[164:165], s[48:49], 0, v[0:1]
	s_mov_b32 m0, s96
	ds_read_b128 v[186:189], v169 offset:16384
	ds_read_b128 v[190:193], v169 offset:17408
	ds_read_b128 v[194:197], v169 offset:18432
	ds_read_b128 v[198:201], v169 offset:19456
	ds_read_b128 v[202:205], v169 offset:20480
	ds_read_b128 v[222:225], v169 offset:21504
	ds_read_b128 v[226:229], v169 offset:22528
	ds_read_b128 v[230:233], v169 offset:23552
	global_load_lds_dwordx4 v[164:165], off
	s_add_i32 m0, s96, 0x2000
	s_add_u32 s96, s48, 0x80000
	v_lshl_add_u64 v[234:235], s[48:49], 0, v[130:131]
	s_addc_u32 s97, s49, 0
	s_add_i32 s75, s75, s69
	global_load_lds_dwordx4 v[234:235], off
	v_lshl_add_u64 v[236:237], s[96:97], 0, v[0:1]
	s_mov_b32 m0, s75
	v_lshl_add_u64 v[238:239], s[50:51], 0, v[132:133]
	global_load_lds_dwordx4 v[236:237], off
	v_lshl_add_u64 v[236:237], s[96:97], 0, v[130:131]
	s_add_i32 m0, s75, 0x2000
	s_nop 0
	global_load_lds_dwordx4 v[236:237], off
	v_lshl_add_u64 v[236:237], s[50:51], 0, v[134:135]
	s_mov_b32 m0, s74
	s_nop 0
	global_load_lds_dwordx4 v[236:237], off
	s_mov_b32 m0, s65
	s_nop 0
	global_load_lds_dwordx4 v[238:239], off
	s_waitcnt vmcnt(8)
	s_waitcnt lgkmcnt(0)
	s_barrier
; #define PG8_STAGE(bufoff, gbase, voff) do { _Pragma("unroll") for (int _i = 0; _i < 2; ++_i) \
;         __builtin_amdgcn_global_load_lds((const unsigned*)((const char*)(gbase) + (voff)[_i]), (LAS unsigned*)(lds + (bufoff) + ldsw + _i * 8192), 16, 0, 0); } while (0)
; #define PG8_LDA(dst, b, h) do { _Pragma("unroll") for (int m = 0; m < 4; ++m) _Pragma("unroll") for (int k = 0; k < 2; ++k) dst[m][k] = *(const LAS bf16x8*)(lds + PG8_SA(b, h) + aoff + m * 2048 + k * 1024); } while (0)
; #define PG8_LDB(dst, b, h) do { _Pragma("unroll") for (int n = 0; n < 2; ++n) _Pragma("unroll") for (int k = 0; k < 2; ++k) dst[n][k] = *(const LAS bf16x8*)(lds + PG8_SB(b, h) + boff + n * 2048 + k * 1024); } while (0)
; #define PG8_MMA(ai, bj, At, Bt) do { __builtin_amdgcn_s_setprio(1); _Pragma("unroll") for (int m = 0; m < 4; ++m) _Pragma("unroll") for (int n = 0; n < 2; ++n) _Pragma("unroll") for (int k = 0; k < 2; ++k) \
;         acc[ai][bj][m][n] = __builtin_amdgcn_mfma_f32_16x16x32_bf16(Bt[n][k], At[m][k], acc[ai][bj][m][n], 0, 0, 0); __builtin_amdgcn_s_setprio(0); } while (0)
; #define PG8_WAIT_V(n) asm volatile("s_waitcnt vmcnt(" #n ")" ::: "memory")
; #define PG8_WAIT_L(n) asm volatile("s_waitcnt lgkmcnt(" #n ")" ::: "memory")
; #define PG8_BAR __builtin_amdgcn_s_barrier()
; #define PG8_SCHED __builtin_amdgcn_sched_barrier(0)
; template <class Epi, class Sched, bool ALIGN_EPI = false, bool SP2 = false>
; __device__ __forceinline__ void gemm_phase(LAS unsigned char* lds, const Gemm g, const Sched& S, const Epi& E) {
;     ...
;             PG8_WAIT_V(8); PG8_WAIT_L(0); PG8_BAR; PG8_MMA(1, 0, At, B0); PG8_MMA(1, 1, At, B1); PG8_BAR; PG8_SCHED;
;             PG8_LDB(B0, 1, 0); PG8_LDB(B1, 1, 1); PG8_SCHED; PG8_LDA(At, 1, 0); PG8_STAGE(PG8_SA(0, 1), a2 + hstep, voffA);
;             PG8_WAIT_V(8); PG8_WAIT_L(0); PG8_BAR; PG8_MMA(0, 0, At, B0); PG8_MMA(0, 1, At, B1); PG8_BAR; PG8_SCHED;
	s_setprio 1
	s_waitcnt lgkmcnt(0)
	v_mfma_f32_16x16x32_bf16 v[26:29], v[140:143], v[186:189], v[26:29]
	v_mfma_f32_16x16x32_bf16 v[18:21], v[148:151], v[186:189], v[18:21]
	v_mfma_f32_16x16x32_bf16 v[62:65], v[140:143], v[194:197], v[62:65]
	v_mfma_f32_16x16x32_bf16 v[58:61], v[148:151], v[194:197], v[58:61]
	v_mfma_f32_16x16x32_bf16 v[54:57], v[140:143], v[202:205], v[54:57]
	v_mfma_f32_16x16x32_bf16 v[50:53], v[148:151], v[202:205], v[50:53]
	v_mfma_f32_16x16x32_bf16 v[30:33], v[140:143], v[226:229], v[30:33]
	v_mfma_f32_16x16x32_bf16 v[22:25], v[148:151], v[226:229], v[22:25]
	v_mfma_f32_16x16x32_bf16 v[26:29], v[144:147], v[190:193], v[26:29]
	v_mfma_f32_16x16x32_bf16 v[18:21], v[152:155], v[190:193], v[18:21]
	v_mfma_f32_16x16x32_bf16 v[62:65], v[144:147], v[198:201], v[62:65]
	v_mfma_f32_16x16x32_bf16 v[58:61], v[152:155], v[198:201], v[58:61]
	v_mfma_f32_16x16x32_bf16 v[54:57], v[144:147], v[222:225], v[54:57]
	v_mfma_f32_16x16x32_bf16 v[50:53], v[152:155], v[222:225], v[50:53]
	v_mfma_f32_16x16x32_bf16 v[30:33], v[144:147], v[230:233], v[30:33]
	v_mfma_f32_16x16x32_bf16 v[22:25], v[152:155], v[230:233], v[22:25]
	v_mfma_f32_16x16x32_bf16 v[10:13], v[156:159], v[186:189], v[10:13]
	v_mfma_f32_16x16x32_bf16 v[2:5], v[170:173], v[186:189], v[2:5]
	v_mfma_f32_16x16x32_bf16 v[46:49], v[156:159], v[194:197], v[46:49]
	v_mfma_f32_16x16x32_bf16 v[42:45], v[170:173], v[194:197], v[42:45]
	v_mfma_f32_16x16x32_bf16 v[38:41], v[156:159], v[202:205], v[38:41]
	v_mfma_f32_16x16x32_bf16 v[34:37], v[170:173], v[202:205], v[34:37]
	v_mfma_f32_16x16x32_bf16 v[14:17], v[156:159], v[226:229], v[14:17]
	v_mfma_f32_16x16x32_bf16 v[6:9], v[170:173], v[226:229], v[6:9]
	v_mfma_f32_16x16x32_bf16 v[10:13], v[160:163], v[190:193], v[10:13]
	v_mfma_f32_16x16x32_bf16 v[2:5], v[174:177], v[190:193], v[2:5]
	v_mfma_f32_16x16x32_bf16 v[46:49], v[160:163], v[198:201], v[46:49]
	v_mfma_f32_16x16x32_bf16 v[42:45], v[174:177], v[198:201], v[42:45]
	v_mfma_f32_16x16x32_bf16 v[38:41], v[160:163], v[222:225], v[38:41]
	v_mfma_f32_16x16x32_bf16 v[34:37], v[174:177], v[222:225], v[34:37]
	v_mfma_f32_16x16x32_bf16 v[14:17], v[160:163], v[230:233], v[14:17]
	v_mfma_f32_16x16x32_bf16 v[6:9], v[174:177], v[230:233], v[6:9]
	s_setprio 0
	s_barrier
	s_add_i32 s75, 0, 0x18000
	s_add_i32 s96, 0, 0x1c000
	v_add_u32_e32 v152, s75, v168
	v_add_u32_e32 v174, s96, v168
	ds_read_b128 v[140:143], v152
	ds_read_b128 v[144:147], v152 offset:1024
	ds_read_b128 v[148:151], v152 offset:2048
	ds_read_b128 v[152:155], v152 offset:3072
	ds_read_b128 v[156:159], v174
	ds_read_b128 v[160:163], v174 offset:1024
	ds_read_b128 v[170:173], v174 offset:2048
	ds_read_b128 v[174:177], v174 offset:3072
	s_add_u32 s50, s50, 0x80000
	s_addc_u32 s51, s51, 0
	s_mov_b32 m0, s76
	v_lshl_add_u64 v[240:241], s[50:51], 0, v[134:135]
	ds_read_b128 v[186:189], v169 offset:32768
	ds_read_b128 v[190:193], v169 offset:33792
	ds_read_b128 v[194:197], v169 offset:34816
	ds_read_b128 v[198:201], v169 offset:35840
	ds_read_b128 v[202:205], v169 offset:36864
	ds_read_b128 v[222:225], v169 offset:37888
	ds_read_b128 v[226:229], v169 offset:38912
	ds_read_b128 v[230:233], v169 offset:39936
	global_load_lds_dwordx4 v[240:241], off
	v_lshl_add_u64 v[240:241], s[50:51], 0, v[132:133]
	s_mov_b32 m0, s77
	s_nop 0
	global_load_lds_dwordx4 v[240:241], off
	s_waitcnt vmcnt(8)
	s_waitcnt lgkmcnt(0)
	s_barrier
	s_setprio 1
	s_waitcnt lgkmcnt(0)
	v_mfma_f32_16x16x32_bf16 v[122:125], v[140:143], v[186:189], v[122:125]
	v_mfma_f32_16x16x32_bf16 v[114:117], v[148:151], v[186:189], v[114:117]
	v_mfma_f32_16x16x32_bf16 v[102:105], v[140:143], v[194:197], v[102:105]
	v_mfma_f32_16x16x32_bf16 v[98:101], v[148:151], v[194:197], v[98:101]
	v_mfma_f32_16x16x32_bf16 v[94:97], v[140:143], v[202:205], v[94:97]
	v_mfma_f32_16x16x32_bf16 v[78:81], v[148:151], v[202:205], v[78:81]
	v_mfma_f32_16x16x32_bf16 v[126:129], v[140:143], v[226:229], v[126:129]
	v_mfma_f32_16x16x32_bf16 v[118:121], v[148:151], v[226:229], v[118:121]
	v_mfma_f32_16x16x32_bf16 v[122:125], v[144:147], v[190:193], v[122:125]
	v_mfma_f32_16x16x32_bf16 v[114:117], v[152:155], v[190:193], v[114:117]
	v_mfma_f32_16x16x32_bf16 v[102:105], v[144:147], v[198:201], v[102:105]
	v_mfma_f32_16x16x32_bf16 v[98:101], v[152:155], v[198:201], v[98:101]
	v_mfma_f32_16x16x32_bf16 v[94:97], v[144:147], v[222:225], v[94:97]
	v_mfma_f32_16x16x32_bf16 v[78:81], v[152:155], v[222:225], v[78:81]
	v_mfma_f32_16x16x32_bf16 v[126:129], v[144:147], v[230:233], v[126:129]
	v_mfma_f32_16x16x32_bf16 v[118:121], v[152:155], v[230:233], v[118:121]
	v_mfma_f32_16x16x32_bf16 v[106:109], v[156:159], v[186:189], v[106:109]
	v_mfma_f32_16x16x32_bf16 v[86:89], v[170:173], v[186:189], v[86:89]
	v_mfma_f32_16x16x32_bf16 v[82:85], v[156:159], v[194:197], v[82:85]
	v_mfma_f32_16x16x32_bf16 v[74:77], v[170:173], v[194:197], v[74:77]
	v_mfma_f32_16x16x32_bf16 v[70:73], v[156:159], v[202:205], v[70:73]
	v_mfma_f32_16x16x32_bf16 v[66:69], v[170:173], v[202:205], v[66:69]
	v_mfma_f32_16x16x32_bf16 v[110:113], v[156:159], v[226:229], v[110:113]
	v_mfma_f32_16x16x32_bf16 v[90:93], v[170:173], v[226:229], v[90:93]
	v_mfma_f32_16x16x32_bf16 v[106:109], v[160:163], v[190:193], v[106:109]
	v_mfma_f32_16x16x32_bf16 v[86:89], v[174:177], v[190:193], v[86:89]
	v_mfma_f32_16x16x32_bf16 v[82:85], v[160:163], v[198:201], v[82:85]
	v_mfma_f32_16x16x32_bf16 v[74:77], v[174:177], v[198:201], v[74:77]
	v_mfma_f32_16x16x32_bf16 v[70:73], v[160:163], v[222:225], v[70:73]
	v_mfma_f32_16x16x32_bf16 v[66:69], v[174:177], v[222:225], v[66:69]
	v_mfma_f32_16x16x32_bf16 v[110:113], v[160:163], v[230:233], v[110:113]
	v_mfma_f32_16x16x32_bf16 v[90:93], v[174:177], v[230:233], v[90:93]
	s_setprio 0
	s_barrier
; #define PG8_STAGE(bufoff, gbase, voff) do { _Pragma("unroll") for (int _i = 0; _i < 2; ++_i) \
;         __builtin_amdgcn_global_load_lds((const unsigned*)((const char*)(gbase) + (voff)[_i]), (LAS unsigned*)(lds + (bufoff) + ldsw + _i * 8192), 16, 0, 0); } while (0)
; #define PG8_LDA(dst, b, h) do { _Pragma("unroll") for (int m = 0; m < 4; ++m) _Pragma("unroll") for (int k = 0; k < 2; ++k) dst[m][k] = *(const LAS bf16x8*)(lds + PG8_SA(b, h) + aoff + m * 2048 + k * 1024); } while (0)
; #define PG8_MMA(ai, bj, At, Bt) do { __builtin_amdgcn_s_setprio(1); _Pragma("unroll") for (int m = 0; m < 4; ++m) _Pragma("unroll") for (int n = 0; n < 2; ++n) _Pragma("unroll") for (int k = 0; k < 2; ++k) \
;         acc[ai][bj][m][n] = __builtin_amdgcn_mfma_f32_16x16x32_bf16(Bt[n][k], At[m][k], acc[ai][bj][m][n], 0, 0, 0); __builtin_amdgcn_s_setprio(0); } while (0)
; #define PG8_WAIT_V(n) asm volatile("s_waitcnt vmcnt(" #n ")" ::: "memory")
; #define PG8_WAIT_L(n) asm volatile("s_waitcnt lgkmcnt(" #n ")" ::: "memory")
; #define PG8_BAR __builtin_amdgcn_s_barrier()
; #define PG8_SCHED __builtin_amdgcn_sched_barrier(0)
; template <class Epi, class Sched, bool ALIGN_EPI = false, bool SP2 = false>
; __device__ __forceinline__ void gemm_phase(LAS unsigned char* lds, const Gemm g, const Sched& S, const Epi& E) {
;     ...
;             PG8_LDA(At, 1, 1); PG8_STAGE(PG8_SB(1, 0), b3, voffB); PG8_STAGE(PG8_SB(1, 1), b3 + hstep, voffB); PG8_STAGE(PG8_SA(1, 0), a3, voffA);
;             PG8_WAIT_V(8); PG8_WAIT_L(0); PG8_BAR; PG8_MMA(1, 0, At, B0); PG8_MMA(1, 1, At, B1); PG8_BAR; PG8_SCHED;
;     ...
;         if constexpr (ALIGN_EPI) { if (wr == 0) PG8_BAR; }
	s_add_i32 s50, s75, s69
	v_lshl_add_u64 v[164:165], v[164:165], 0, s[26:27]
	s_mov_b32 m0, s50
	ds_read_b128 v[186:189], v169 offset:49152
	ds_read_b128 v[190:193], v169 offset:50176
	ds_read_b128 v[194:197], v169 offset:51200
	ds_read_b128 v[198:201], v169 offset:52224
	ds_read_b128 v[202:205], v169 offset:53248
	ds_read_b128 v[222:225], v169 offset:54272
	ds_read_b128 v[226:229], v169 offset:55296
	ds_read_b128 v[230:233], v169 offset:56320
	global_load_lds_dwordx4 v[164:165], off
	s_add_i32 m0, s50, 0x2000
	s_add_u32 s48, s48, 0x80080
	v_lshl_add_u64 v[164:165], v[234:235], 0, s[26:27]
	s_addc_u32 s49, s49, 0
	s_add_i32 s50, s96, s69
	global_load_lds_dwordx4 v[164:165], off
	v_lshl_add_u64 v[164:165], s[48:49], 0, v[0:1]
	s_mov_b32 m0, s50
	s_nop 0
	global_load_lds_dwordx4 v[164:165], off
	v_lshl_add_u64 v[164:165], s[48:49], 0, v[130:131]
	s_add_i32 m0, s50, 0x2000
	s_nop 0
	global_load_lds_dwordx4 v[164:165], off
	v_lshl_add_u64 v[164:165], v[236:237], 0, s[26:27]
	s_mov_b32 m0, s71
	s_nop 0
	global_load_lds_dwordx4 v[164:165], off
	v_lshl_add_u64 v[164:165], v[238:239], 0, s[26:27]
	s_mov_b32 m0, s89
	s_nop 0
	global_load_lds_dwordx4 v[164:165], off
	s_waitcnt vmcnt(8)
	s_waitcnt lgkmcnt(0)
	s_barrier
	s_setprio 1
	s_waitcnt lgkmcnt(0)
	v_mfma_f32_16x16x32_bf16 v[26:29], v[140:143], v[186:189], v[26:29]
	v_mfma_f32_16x16x32_bf16 v[18:21], v[148:151], v[186:189], v[18:21]
	v_mfma_f32_16x16x32_bf16 v[62:65], v[140:143], v[194:197], v[62:65]
	v_mfma_f32_16x16x32_bf16 v[58:61], v[148:151], v[194:197], v[58:61]
	v_mfma_f32_16x16x32_bf16 v[54:57], v[140:143], v[202:205], v[54:57]
	v_mfma_f32_16x16x32_bf16 v[50:53], v[148:151], v[202:205], v[50:53]
	v_mfma_f32_16x16x32_bf16 v[30:33], v[140:143], v[226:229], v[30:33]
	v_mfma_f32_16x16x32_bf16 v[22:25], v[148:151], v[226:229], v[22:25]
	v_mfma_f32_16x16x32_bf16 v[26:29], v[144:147], v[190:193], v[26:29]
	v_mfma_f32_16x16x32_bf16 v[18:21], v[152:155], v[190:193], v[18:21]
	v_mfma_f32_16x16x32_bf16 v[62:65], v[144:147], v[198:201], v[62:65]
	v_mfma_f32_16x16x32_bf16 v[58:61], v[152:155], v[198:201], v[58:61]
	v_mfma_f32_16x16x32_bf16 v[54:57], v[144:147], v[222:225], v[54:57]
	v_mfma_f32_16x16x32_bf16 v[50:53], v[152:155], v[222:225], v[50:53]
	v_mfma_f32_16x16x32_bf16 v[30:33], v[144:147], v[230:233], v[30:33]
	v_mfma_f32_16x16x32_bf16 v[22:25], v[152:155], v[230:233], v[22:25]
	v_mfma_f32_16x16x32_bf16 v[10:13], v[156:159], v[186:189], v[10:13]
	v_mfma_f32_16x16x32_bf16 v[2:5], v[170:173], v[186:189], v[2:5]
	v_mfma_f32_16x16x32_bf16 v[46:49], v[156:159], v[194:197], v[46:49]
	v_mfma_f32_16x16x32_bf16 v[42:45], v[170:173], v[194:197], v[42:45]
	v_mfma_f32_16x16x32_bf16 v[38:41], v[156:159], v[202:205], v[38:41]
	v_mfma_f32_16x16x32_bf16 v[34:37], v[170:173], v[202:205], v[34:37]
	v_mfma_f32_16x16x32_bf16 v[14:17], v[156:159], v[226:229], v[14:17]
	v_mfma_f32_16x16x32_bf16 v[6:9], v[170:173], v[226:229], v[6:9]
	v_mfma_f32_16x16x32_bf16 v[10:13], v[160:163], v[190:193], v[10:13]
	v_mfma_f32_16x16x32_bf16 v[2:5], v[174:177], v[190:193], v[2:5]
	v_mfma_f32_16x16x32_bf16 v[46:49], v[160:163], v[198:201], v[46:49]
	v_mfma_f32_16x16x32_bf16 v[42:45], v[174:177], v[198:201], v[42:45]
	v_mfma_f32_16x16x32_bf16 v[38:41], v[160:163], v[222:225], v[38:41]
	v_mfma_f32_16x16x32_bf16 v[34:37], v[174:177], v[222:225], v[34:37]
	v_mfma_f32_16x16x32_bf16 v[14:17], v[160:163], v[230:233], v[14:17]
	v_mfma_f32_16x16x32_bf16 v[6:9], v[174:177], v[230:233], v[6:9]
	s_setprio 0
	s_barrier
	s_add_i32 s54, s54, 2
	s_add_u32 vcc_hi, vcc_hi, 0x100
	s_addc_u32 s62, s62, 0
	s_add_u32 s40, s40, 0x100
	s_addc_u32 s41, s41, 0
	s_cmp_gt_u32 s54, 29
	s_cbranch_scc0 .LBB0_56
	v_readlane_b32 s40, v255, 7
	v_readlane_b32 s41, v255, 8
	s_and_b64 vcc, exec, s[40:41]
	s_cbranch_vccz .LBB0_59
	s_barrier

; #define PG8_STAGE(bufoff, gbase, voff) do { _Pragma("unroll") for (int _i = 0; _i < 2; ++_i) \
;         __builtin_amdgcn_global_load_lds((const unsigned*)((const char*)(gbase) + (voff)[_i]), (LAS unsigned*)(lds + (bufoff) + ldsw + _i * 8192), 16, 0, 0); } while (0)
; #define PG8_LDA(dst, b, h) do { _Pragma("unroll") for (int m = 0; m < 4; ++m) _Pragma("unroll") for (int k = 0; k < 2; ++k) dst[m][k] = *(const LAS bf16x8*)(lds + PG8_SA(b, h) + aoff + m * 2048 + k * 1024); } while (0)
; #define PG8_LDB(dst, b, h) do { _Pragma("unroll") for (int n = 0; n < 2; ++n) _Pragma("unroll") for (int k = 0; k < 2; ++k) dst[n][k] = *(const LAS bf16x8*)(lds + PG8_SB(b, h) + boff + n * 2048 + k * 1024); } while (0)
; #define PG8_MMA(ai, bj, At, Bt) do { __builtin_amdgcn_s_setprio(1); _Pragma("unroll") for (int m = 0; m < 4; ++m) _Pragma("unroll") for (int n = 0; n < 2; ++n) _Pragma("unroll") for (int k = 0; k < 2; ++k) \
;         acc[ai][bj][m][n] = __builtin_amdgcn_mfma_f32_16x16x32_bf16(Bt[n][k], At[m][k], acc[ai][bj][m][n], 0, 0, 0); __builtin_amdgcn_s_setprio(0); } while (0)
; #define PG8_WAIT_V(n) asm volatile("s_waitcnt vmcnt(" #n ")" ::: "memory")
; #define PG8_WAIT_L(n) asm volatile("s_waitcnt lgkmcnt(" #n ")" ::: "memory")
; #define PG8_BAR __builtin_amdgcn_s_barrier()
; #define PG8_SCHED __builtin_amdgcn_sched_barrier(0)
; template <class Epi, class Sched, bool ALIGN_EPI = false, bool SP2 = false>
; __device__ __forceinline__ void gemm_phase(LAS unsigned char* lds, const Gemm g, const Sched& S, const Epi& E) {
;     ...
;             PG8_LDB(B0, 0, 0); PG8_LDB(B1, 0, 1); PG8_SCHED; PG8_LDA(At, 0, 0); PG8_STAGE(PG8_SA(1, 1), a1 + hstep, voffA);
;             PG8_WAIT_V(8); PG8_WAIT_L(0); PG8_BAR; PG8_MMA(0, 0, At, B0); PG8_MMA(0, 1, At, B1); PG8_BAR; PG8_SCHED;
;             PG8_LDA(At, 0, 1); PG8_STAGE(PG8_SB(0, 0), b2, voffB); PG8_STAGE(PG8_SB(0, 1), b2 + hstep, voffB); PG8_STAGE(PG8_SA(0, 0), a2, voffA);
;             PG8_WAIT_V(8); PG8_WAIT_L(0); PG8_BAR; PG8_MMA(1, 0, At, B0); PG8_MMA(1, 1, At, B1); PG8_BAR; PG8_SCHED;
.LBB0_90:
	s_add_i32 s54, s14, 2
	s_add_u32 s75, s12, 0x80
	s_addc_u32 s15, s13, 0
	s_add_i32 s78, 0, 0x10000
	s_cmp_eq_u32 s66, s14
	s_cselect_b32 s15, s1, s15
	s_cselect_b32 s14, s0, s75
	s_cselect_b32 s81, s11, s77
	s_cselect_b32 s80, s10, s62
	s_add_i32 s75, 0, 0x14000
	v_add_u32_e32 v152, s78, v141
	v_add_u32_e32 v168, s75, v141
	ds_read_b128 v[136:139], v152
	ds_read_b128 v[144:147], v152 offset:1024
	ds_read_b128 v[148:151], v152 offset:2048
	ds_read_b128 v[152:155], v152 offset:3072
	ds_read_b128 v[156:159], v168
	ds_read_b128 v[160:163], v168 offset:1024
	ds_read_b128 v[164:167], v168 offset:2048
	ds_read_b128 v[168:171], v168 offset:3072
	v_lshl_add_u64 v[176:177], s[12:13], 0, v[134:135]
	s_add_i32 m0, s48, 0xc000
	ds_read_b128 v[172:175], v143
	ds_read_b128 v[186:189], v143 offset:1024
	ds_read_b128 v[190:193], v143 offset:2048
	ds_read_b128 v[194:197], v143 offset:3072
	ds_read_b128 v[198:201], v143 offset:4096
	ds_read_b128 v[202:205], v143 offset:5120
	ds_read_b128 v[222:225], v143 offset:6144
	ds_read_b128 v[226:229], v143 offset:7168
	global_load_lds_dwordx4 v[176:177], off
	v_lshl_add_u64 v[176:177], s[12:13], 0, v[132:133]
	s_add_i32 m0, s48, 0xe000
	s_nop 0
	global_load_lds_dwordx4 v[176:177], off
	s_waitcnt vmcnt(8)
	s_waitcnt lgkmcnt(0)
	s_barrier
	s_setprio 1
	s_waitcnt lgkmcnt(0)
	v_mfma_f32_16x16x32_bf16 v[126:129], v[136:139], v[172:175], v[126:129]
	v_mfma_f32_16x16x32_bf16 v[122:125], v[148:151], v[172:175], v[122:125]
	v_mfma_f32_16x16x32_bf16 v[110:113], v[136:139], v[190:193], v[110:113]
	v_mfma_f32_16x16x32_bf16 v[106:109], v[148:151], v[190:193], v[106:109]
	v_mfma_f32_16x16x32_bf16 v[94:97], v[136:139], v[198:201], v[94:97]
	v_mfma_f32_16x16x32_bf16 v[90:93], v[148:151], v[198:201], v[90:93]
	v_mfma_f32_16x16x32_bf16 v[78:81], v[136:139], v[222:225], v[78:81]
	v_mfma_f32_16x16x32_bf16 v[74:77], v[148:151], v[222:225], v[74:77]
	v_mfma_f32_16x16x32_bf16 v[126:129], v[144:147], v[186:189], v[126:129]
	v_mfma_f32_16x16x32_bf16 v[122:125], v[152:155], v[186:189], v[122:125]
	v_mfma_f32_16x16x32_bf16 v[110:113], v[144:147], v[194:197], v[110:113]
	v_mfma_f32_16x16x32_bf16 v[106:109], v[152:155], v[194:197], v[106:109]
	v_mfma_f32_16x16x32_bf16 v[94:97], v[144:147], v[202:205], v[94:97]
	v_mfma_f32_16x16x32_bf16 v[90:93], v[152:155], v[202:205], v[90:93]
	v_mfma_f32_16x16x32_bf16 v[78:81], v[144:147], v[226:229], v[78:81]
	v_mfma_f32_16x16x32_bf16 v[74:77], v[152:155], v[226:229], v[74:77]
	v_mfma_f32_16x16x32_bf16 v[118:121], v[156:159], v[172:175], v[118:121]
	v_mfma_f32_16x16x32_bf16 v[114:117], v[164:167], v[172:175], v[114:117]
	v_mfma_f32_16x16x32_bf16 v[102:105], v[156:159], v[190:193], v[102:105]
	v_mfma_f32_16x16x32_bf16 v[98:101], v[164:167], v[190:193], v[98:101]
	v_mfma_f32_16x16x32_bf16 v[86:89], v[156:159], v[198:201], v[86:89]
	v_mfma_f32_16x16x32_bf16 v[82:85], v[164:167], v[198:201], v[82:85]
	v_mfma_f32_16x16x32_bf16 v[70:73], v[156:159], v[222:225], v[70:73]
	v_mfma_f32_16x16x32_bf16 v[66:69], v[164:167], v[222:225], v[66:69]
	v_mfma_f32_16x16x32_bf16 v[118:121], v[160:163], v[186:189], v[118:121]
	v_mfma_f32_16x16x32_bf16 v[114:117], v[168:171], v[186:189], v[114:117]
	v_mfma_f32_16x16x32_bf16 v[102:105], v[160:163], v[194:197], v[102:105]
	v_mfma_f32_16x16x32_bf16 v[98:101], v[168:171], v[194:197], v[98:101]
	v_mfma_f32_16x16x32_bf16 v[86:89], v[160:163], v[202:205], v[86:89]
	v_mfma_f32_16x16x32_bf16 v[82:85], v[168:171], v[202:205], v[82:85]
	v_mfma_f32_16x16x32_bf16 v[70:73], v[160:163], v[226:229], v[70:73]
	v_mfma_f32_16x16x32_bf16 v[66:69], v[168:171], v[226:229], v[66:69]
	s_setprio 0
	s_barrier
	s_add_i32 s78, s78, s28
	v_lshl_add_u64 v[176:177], s[80:81], 0, v[0:1]
	s_mov_b32 m0, s78
	ds_read_b128 v[172:175], v143 offset:16384
	ds_read_b128 v[186:189], v143 offset:17408
	ds_read_b128 v[190:193], v143 offset:18432
	ds_read_b128 v[194:197], v143 offset:19456
	ds_read_b128 v[198:201], v143 offset:20480
	ds_read_b128 v[202:205], v143 offset:21504
	ds_read_b128 v[222:225], v143 offset:22528
	ds_read_b128 v[226:229], v143 offset:23552
	global_load_lds_dwordx4 v[176:177], off
	s_add_i32 m0, s78, 0x2000
	v_lshl_add_u64 v[230:231], s[80:81], 0, v[130:131]
	s_add_u32 s80, s80, s24
	s_addc_u32 s81, s81, 0
	s_add_i32 s75, s75, s28
	global_load_lds_dwordx4 v[230:231], off
	v_lshl_add_u64 v[232:233], s[80:81], 0, v[0:1]
	s_mov_b32 m0, s75
	v_lshl_add_u64 v[234:235], s[80:81], 0, v[130:131]
	global_load_lds_dwordx4 v[232:233], off
	s_add_i32 m0, s75, 0x2000
	v_lshl_add_u64 v[236:237], s[14:15], 0, v[0:1]
	global_load_lds_dwordx4 v[234:235], off
	s_mov_b32 m0, s48
	v_lshl_add_u64 v[238:239], s[14:15], 0, v[130:131]
	global_load_lds_dwordx4 v[236:237], off
	s_mov_b32 m0, s49
	s_nop 0
	global_load_lds_dwordx4 v[238:239], off
	s_waitcnt vmcnt(8)
	s_waitcnt lgkmcnt(0)
	s_barrier
; #define PG8_STAGE(bufoff, gbase, voff) do { _Pragma("unroll") for (int _i = 0; _i < 2; ++_i) \
;         __builtin_amdgcn_global_load_lds((const unsigned*)((const char*)(gbase) + (voff)[_i]), (LAS unsigned*)(lds + (bufoff) + ldsw + _i * 8192), 16, 0, 0); } while (0)
; #define PG8_LDA(dst, b, h) do { _Pragma("unroll") for (int m = 0; m < 4; ++m) _Pragma("unroll") for (int k = 0; k < 2; ++k) dst[m][k] = *(const LAS bf16x8*)(lds + PG8_SA(b, h) + aoff + m * 2048 + k * 1024); } while (0)
; #define PG8_LDB(dst, b, h) do { _Pragma("unroll") for (int n = 0; n < 2; ++n) _Pragma("unroll") for (int k = 0; k < 2; ++k) dst[n][k] = *(const LAS bf16x8*)(lds + PG8_SB(b, h) + boff + n * 2048 + k * 1024); } while (0)
; #define PG8_MMA(ai, bj, At, Bt) do { __builtin_amdgcn_s_setprio(1); _Pragma("unroll") for (int m = 0; m < 4; ++m) _Pragma("unroll") for (int n = 0; n < 2; ++n) _Pragma("unroll") for (int k = 0; k < 2; ++k) \
;         acc[ai][bj][m][n] = __builtin_amdgcn_mfma_f32_16x16x32_bf16(Bt[n][k], At[m][k], acc[ai][bj][m][n], 0, 0, 0); __builtin_amdgcn_s_setprio(0); } while (0)
; #define PG8_WAIT_V(n) asm volatile("s_waitcnt vmcnt(" #n ")" ::: "memory")
; #define PG8_WAIT_L(n) asm volatile("s_waitcnt lgkmcnt(" #n ")" ::: "memory")
; #define PG8_BAR __builtin_amdgcn_s_barrier()
; #define PG8_SCHED __builtin_amdgcn_sched_barrier(0)
; template <class Epi, class Sched, bool ALIGN_EPI = false, bool SP2 = false>
; __device__ __forceinline__ void gemm_phase(LAS unsigned char* lds, const Gemm g, const Sched& S, const Epi& E) {
;     ...
;             PG8_WAIT_V(8); PG8_WAIT_L(0); PG8_BAR; PG8_MMA(1, 0, At, B0); PG8_MMA(1, 1, At, B1); PG8_BAR; PG8_SCHED;
;             PG8_LDB(B0, 1, 0); PG8_LDB(B1, 1, 1); PG8_SCHED; PG8_LDA(At, 1, 0); PG8_STAGE(PG8_SA(0, 1), a2 + hstep, voffA);
;             PG8_WAIT_V(8); PG8_WAIT_L(0); PG8_BAR; PG8_MMA(0, 0, At, B0); PG8_MMA(0, 1, At, B1); PG8_BAR; PG8_SCHED;
	s_setprio 1
	s_waitcnt lgkmcnt(0)
	v_mfma_f32_16x16x32_bf16 v[62:65], v[136:139], v[172:175], v[62:65]
	v_mfma_f32_16x16x32_bf16 v[58:61], v[148:151], v[172:175], v[58:61]
	v_mfma_f32_16x16x32_bf16 v[46:49], v[136:139], v[190:193], v[46:49]
	v_mfma_f32_16x16x32_bf16 v[42:45], v[148:151], v[190:193], v[42:45]
	v_mfma_f32_16x16x32_bf16 v[30:33], v[136:139], v[198:201], v[30:33]
	v_mfma_f32_16x16x32_bf16 v[26:29], v[148:151], v[198:201], v[26:29]
	v_mfma_f32_16x16x32_bf16 v[14:17], v[136:139], v[222:225], v[14:17]
	v_mfma_f32_16x16x32_bf16 v[10:13], v[148:151], v[222:225], v[10:13]
	v_mfma_f32_16x16x32_bf16 v[62:65], v[144:147], v[186:189], v[62:65]
	v_mfma_f32_16x16x32_bf16 v[58:61], v[152:155], v[186:189], v[58:61]
	v_mfma_f32_16x16x32_bf16 v[46:49], v[144:147], v[194:197], v[46:49]
	v_mfma_f32_16x16x32_bf16 v[42:45], v[152:155], v[194:197], v[42:45]
	v_mfma_f32_16x16x32_bf16 v[30:33], v[144:147], v[202:205], v[30:33]
	v_mfma_f32_16x16x32_bf16 v[26:29], v[152:155], v[202:205], v[26:29]
	v_mfma_f32_16x16x32_bf16 v[14:17], v[144:147], v[226:229], v[14:17]
	v_mfma_f32_16x16x32_bf16 v[10:13], v[152:155], v[226:229], v[10:13]
	v_mfma_f32_16x16x32_bf16 v[54:57], v[156:159], v[172:175], v[54:57]
	v_mfma_f32_16x16x32_bf16 v[50:53], v[164:167], v[172:175], v[50:53]
	v_mfma_f32_16x16x32_bf16 v[38:41], v[156:159], v[190:193], v[38:41]
	v_mfma_f32_16x16x32_bf16 v[34:37], v[164:167], v[190:193], v[34:37]
	v_mfma_f32_16x16x32_bf16 v[22:25], v[156:159], v[198:201], v[22:25]
	v_mfma_f32_16x16x32_bf16 v[18:21], v[164:167], v[198:201], v[18:21]
	v_mfma_f32_16x16x32_bf16 v[6:9], v[156:159], v[222:225], v[6:9]
	v_mfma_f32_16x16x32_bf16 v[2:5], v[164:167], v[222:225], v[2:5]
	v_mfma_f32_16x16x32_bf16 v[54:57], v[160:163], v[186:189], v[54:57]
	v_mfma_f32_16x16x32_bf16 v[50:53], v[168:171], v[186:189], v[50:53]
	v_mfma_f32_16x16x32_bf16 v[38:41], v[160:163], v[194:197], v[38:41]
	v_mfma_f32_16x16x32_bf16 v[34:37], v[168:171], v[194:197], v[34:37]
	v_mfma_f32_16x16x32_bf16 v[22:25], v[160:163], v[202:205], v[22:25]
	v_mfma_f32_16x16x32_bf16 v[18:21], v[168:171], v[202:205], v[18:21]
	v_mfma_f32_16x16x32_bf16 v[6:9], v[160:163], v[226:229], v[6:9]
	v_mfma_f32_16x16x32_bf16 v[2:5], v[168:171], v[226:229], v[2:5]
	s_setprio 0
	s_barrier
	s_add_i32 s75, 0, 0x18000
	s_add_i32 s78, 0, 0x1c000
	v_add_u32_e32 v152, s75, v141
	v_add_u32_e32 v168, s78, v141
	ds_read_b128 v[136:139], v152
	ds_read_b128 v[144:147], v152 offset:1024
	ds_read_b128 v[148:151], v152 offset:2048
	ds_read_b128 v[152:155], v152 offset:3072
	ds_read_b128 v[156:159], v168
	ds_read_b128 v[160:163], v168 offset:1024
	ds_read_b128 v[164:167], v168 offset:2048
	ds_read_b128 v[168:171], v168 offset:3072
	s_add_u32 s14, s14, s24
	s_addc_u32 s15, s15, 0
	s_mov_b32 m0, s50
	v_lshl_add_u64 v[240:241], s[14:15], 0, v[0:1]
	ds_read_b128 v[172:175], v143 offset:32768
	ds_read_b128 v[186:189], v143 offset:33792
	ds_read_b128 v[190:193], v143 offset:34816
	ds_read_b128 v[194:197], v143 offset:35840
	ds_read_b128 v[198:201], v143 offset:36864
	ds_read_b128 v[202:205], v143 offset:37888
	ds_read_b128 v[222:225], v143 offset:38912
	ds_read_b128 v[226:229], v143 offset:39936
	global_load_lds_dwordx4 v[240:241], off
	v_lshl_add_u64 v[240:241], s[14:15], 0, v[130:131]
	s_mov_b32 m0, s51
	s_nop 0
	global_load_lds_dwordx4 v[240:241], off
	s_waitcnt vmcnt(8)
	s_waitcnt lgkmcnt(0)
	s_barrier
	s_setprio 1
	s_waitcnt lgkmcnt(0)
	v_mfma_f32_16x16x32_bf16 v[126:129], v[136:139], v[172:175], v[126:129]
	v_mfma_f32_16x16x32_bf16 v[122:125], v[148:151], v[172:175], v[122:125]
	v_mfma_f32_16x16x32_bf16 v[110:113], v[136:139], v[190:193], v[110:113]
	v_mfma_f32_16x16x32_bf16 v[106:109], v[148:151], v[190:193], v[106:109]
	v_mfma_f32_16x16x32_bf16 v[94:97], v[136:139], v[198:201], v[94:97]
	v_mfma_f32_16x16x32_bf16 v[90:93], v[148:151], v[198:201], v[90:93]
	v_mfma_f32_16x16x32_bf16 v[78:81], v[136:139], v[222:225], v[78:81]
	v_mfma_f32_16x16x32_bf16 v[74:77], v[148:151], v[222:225], v[74:77]
	v_mfma_f32_16x16x32_bf16 v[126:129], v[144:147], v[186:189], v[126:129]
	v_mfma_f32_16x16x32_bf16 v[122:125], v[152:155], v[186:189], v[122:125]
	v_mfma_f32_16x16x32_bf16 v[110:113], v[144:147], v[194:197], v[110:113]
	v_mfma_f32_16x16x32_bf16 v[106:109], v[152:155], v[194:197], v[106:109]
	v_mfma_f32_16x16x32_bf16 v[94:97], v[144:147], v[202:205], v[94:97]
	v_mfma_f32_16x16x32_bf16 v[90:93], v[152:155], v[202:205], v[90:93]
	v_mfma_f32_16x16x32_bf16 v[78:81], v[144:147], v[226:229], v[78:81]
	v_mfma_f32_16x16x32_bf16 v[74:77], v[152:155], v[226:229], v[74:77]
	v_mfma_f32_16x16x32_bf16 v[118:121], v[156:159], v[172:175], v[118:121]
	v_mfma_f32_16x16x32_bf16 v[114:117], v[164:167], v[172:175], v[114:117]
	v_mfma_f32_16x16x32_bf16 v[102:105], v[156:159], v[190:193], v[102:105]
	v_mfma_f32_16x16x32_bf16 v[98:101], v[164:167], v[190:193], v[98:101]
	v_mfma_f32_16x16x32_bf16 v[86:89], v[156:159], v[198:201], v[86:89]
	v_mfma_f32_16x16x32_bf16 v[82:85], v[164:167], v[198:201], v[82:85]
	v_mfma_f32_16x16x32_bf16 v[70:73], v[156:159], v[222:225], v[70:73]
	v_mfma_f32_16x16x32_bf16 v[66:69], v[164:167], v[222:225], v[66:69]
	v_mfma_f32_16x16x32_bf16 v[118:121], v[160:163], v[186:189], v[118:121]
	v_mfma_f32_16x16x32_bf16 v[114:117], v[168:171], v[186:189], v[114:117]
	v_mfma_f32_16x16x32_bf16 v[102:105], v[160:163], v[194:197], v[102:105]
	v_mfma_f32_16x16x32_bf16 v[98:101], v[168:171], v[194:197], v[98:101]
	v_mfma_f32_16x16x32_bf16 v[86:89], v[160:163], v[202:205], v[86:89]
	v_mfma_f32_16x16x32_bf16 v[82:85], v[168:171], v[202:205], v[82:85]
	v_mfma_f32_16x16x32_bf16 v[70:73], v[160:163], v[226:229], v[70:73]
	v_mfma_f32_16x16x32_bf16 v[66:69], v[168:171], v[226:229], v[66:69]
	s_setprio 0
	s_barrier
; #define PG8_STAGE(bufoff, gbase, voff) do { _Pragma("unroll") for (int _i = 0; _i < 2; ++_i) \
;         __builtin_amdgcn_global_load_lds((const unsigned*)((const char*)(gbase) + (voff)[_i]), (LAS unsigned*)(lds + (bufoff) + ldsw + _i * 8192), 16, 0, 0); } while (0)
; #define PG8_LDA(dst, b, h) do { _Pragma("unroll") for (int m = 0; m < 4; ++m) _Pragma("unroll") for (int k = 0; k < 2; ++k) dst[m][k] = *(const LAS bf16x8*)(lds + PG8_SA(b, h) + aoff + m * 2048 + k * 1024); } while (0)
; #define PG8_MMA(ai, bj, At, Bt) do { __builtin_amdgcn_s_setprio(1); _Pragma("unroll") for (int m = 0; m < 4; ++m) _Pragma("unroll") for (int n = 0; n < 2; ++n) _Pragma("unroll") for (int k = 0; k < 2; ++k) \
;         acc[ai][bj][m][n] = __builtin_amdgcn_mfma_f32_16x16x32_bf16(Bt[n][k], At[m][k], acc[ai][bj][m][n], 0, 0, 0); __builtin_amdgcn_s_setprio(0); } while (0)
; #define PG8_WAIT_V(n) asm volatile("s_waitcnt vmcnt(" #n ")" ::: "memory")
; #define PG8_WAIT_L(n) asm volatile("s_waitcnt lgkmcnt(" #n ")" ::: "memory")
; #define PG8_BAR __builtin_amdgcn_s_barrier()
; #define PG8_SCHED __builtin_amdgcn_sched_barrier(0)
; template <class Epi, class Sched, bool ALIGN_EPI = false, bool SP2 = false>
; __device__ __forceinline__ void gemm_phase(LAS unsigned char* lds, const Gemm g, const Sched& S, const Epi& E) {
;     ...
;             PG8_LDA(At, 1, 1); PG8_STAGE(PG8_SB(1, 0), b3, voffB); PG8_STAGE(PG8_SB(1, 1), b3 + hstep, voffB); PG8_STAGE(PG8_SA(1, 0), a3, voffA);
;             PG8_WAIT_V(8); PG8_WAIT_L(0); PG8_BAR; PG8_MMA(1, 0, At, B0); PG8_MMA(1, 1, At, B1); PG8_BAR; PG8_SCHED;
;     ...
;         if constexpr (ALIGN_EPI) { if (wr == 0) PG8_BAR; }
	s_add_i32 s14, s75, s28
	v_lshl_add_u64 v[176:177], v[176:177], 0, s[26:27]
	s_mov_b32 m0, s14
	ds_read_b128 v[172:175], v143 offset:49152
	ds_read_b128 v[186:189], v143 offset:50176
	ds_read_b128 v[190:193], v143 offset:51200
	ds_read_b128 v[194:197], v143 offset:52224
	ds_read_b128 v[198:201], v143 offset:53248
	ds_read_b128 v[202:205], v143 offset:54272
	ds_read_b128 v[222:225], v143 offset:55296
	ds_read_b128 v[226:229], v143 offset:56320
	global_load_lds_dwordx4 v[176:177], off
	v_lshl_add_u64 v[176:177], v[230:231], 0, s[26:27]
	s_add_i32 m0, s14, 0x2000
	s_add_i32 s14, s78, s28
	global_load_lds_dwordx4 v[176:177], off
	v_lshl_add_u64 v[176:177], v[232:233], 0, s[26:27]
	s_mov_b32 m0, s14
	s_nop 0
	global_load_lds_dwordx4 v[176:177], off
	v_lshl_add_u64 v[176:177], v[234:235], 0, s[26:27]
	s_add_i32 m0, s14, 0x2000
	s_nop 0
	global_load_lds_dwordx4 v[176:177], off
	v_lshl_add_u64 v[176:177], v[236:237], 0, s[26:27]
	s_mov_b32 m0, s67
	s_nop 0
	global_load_lds_dwordx4 v[176:177], off
	v_lshl_add_u64 v[176:177], v[238:239], 0, s[26:27]
	s_mov_b32 m0, s68
	s_nop 0
	global_load_lds_dwordx4 v[176:177], off
	s_waitcnt vmcnt(8)
	s_waitcnt lgkmcnt(0)
	s_barrier
	s_setprio 1
	s_waitcnt lgkmcnt(0)
	v_mfma_f32_16x16x32_bf16 v[62:65], v[136:139], v[172:175], v[62:65]
	v_mfma_f32_16x16x32_bf16 v[58:61], v[148:151], v[172:175], v[58:61]
	v_mfma_f32_16x16x32_bf16 v[46:49], v[136:139], v[190:193], v[46:49]
	v_mfma_f32_16x16x32_bf16 v[42:45], v[148:151], v[190:193], v[42:45]
	v_mfma_f32_16x16x32_bf16 v[30:33], v[136:139], v[198:201], v[30:33]
	v_mfma_f32_16x16x32_bf16 v[26:29], v[148:151], v[198:201], v[26:29]
	v_mfma_f32_16x16x32_bf16 v[14:17], v[136:139], v[222:225], v[14:17]
	v_mfma_f32_16x16x32_bf16 v[10:13], v[148:151], v[222:225], v[10:13]
	v_mfma_f32_16x16x32_bf16 v[62:65], v[144:147], v[186:189], v[62:65]
	v_mfma_f32_16x16x32_bf16 v[58:61], v[152:155], v[186:189], v[58:61]
	v_mfma_f32_16x16x32_bf16 v[46:49], v[144:147], v[194:197], v[46:49]
	v_mfma_f32_16x16x32_bf16 v[42:45], v[152:155], v[194:197], v[42:45]
	v_mfma_f32_16x16x32_bf16 v[30:33], v[144:147], v[202:205], v[30:33]
	v_mfma_f32_16x16x32_bf16 v[26:29], v[152:155], v[202:205], v[26:29]
	v_mfma_f32_16x16x32_bf16 v[14:17], v[144:147], v[226:229], v[14:17]
	v_mfma_f32_16x16x32_bf16 v[10:13], v[152:155], v[226:229], v[10:13]
	v_mfma_f32_16x16x32_bf16 v[54:57], v[156:159], v[172:175], v[54:57]
	v_mfma_f32_16x16x32_bf16 v[50:53], v[164:167], v[172:175], v[50:53]
	v_mfma_f32_16x16x32_bf16 v[38:41], v[156:159], v[190:193], v[38:41]
	v_mfma_f32_16x16x32_bf16 v[34:37], v[164:167], v[190:193], v[34:37]
	v_mfma_f32_16x16x32_bf16 v[22:25], v[156:159], v[198:201], v[22:25]
	v_mfma_f32_16x16x32_bf16 v[18:21], v[164:167], v[198:201], v[18:21]
	v_mfma_f32_16x16x32_bf16 v[6:9], v[156:159], v[222:225], v[6:9]
	v_mfma_f32_16x16x32_bf16 v[2:5], v[164:167], v[222:225], v[2:5]
	v_mfma_f32_16x16x32_bf16 v[54:57], v[160:163], v[186:189], v[54:57]
	v_mfma_f32_16x16x32_bf16 v[50:53], v[168:171], v[186:189], v[50:53]
	v_mfma_f32_16x16x32_bf16 v[38:41], v[160:163], v[194:197], v[38:41]
	v_mfma_f32_16x16x32_bf16 v[34:37], v[168:171], v[194:197], v[34:37]
	v_mfma_f32_16x16x32_bf16 v[22:25], v[160:163], v[202:205], v[22:25]
	v_mfma_f32_16x16x32_bf16 v[18:21], v[168:171], v[202:205], v[18:21]
	v_mfma_f32_16x16x32_bf16 v[6:9], v[160:163], v[226:229], v[6:9]
	v_mfma_f32_16x16x32_bf16 v[2:5], v[168:171], v[226:229], v[2:5]
	s_setprio 0
	s_barrier
	s_add_u32 s62, s62, 0x100
	s_addc_u32 s77, s77, 0
	s_add_u32 s12, s12, 0x100
	s_addc_u32 s13, s13, 0
	s_cmp_ge_u32 s54, s65
	s_mov_b32 s14, s54
	s_cbranch_scc0 .LBB0_90
	s_and_b64 vcc, exec, s[6:7]
	s_cbranch_vccz .LBB0_93
	s_barrier

; #define PG8_STAGE(bufoff, gbase, voff) do { _Pragma("unroll") for (int _i = 0; _i < 2; ++_i) \
;         __builtin_amdgcn_global_load_lds((const unsigned*)((const char*)(gbase) + (voff)[_i]), (LAS unsigned*)(lds + (bufoff) + ldsw + _i * 8192), 16, 0, 0); } while (0)
; #define PG8_LDA(dst, b, h) do { _Pragma("unroll") for (int m = 0; m < 4; ++m) _Pragma("unroll") for (int k = 0; k < 2; ++k) dst[m][k] = *(const LAS bf16x8*)(lds + PG8_SA(b, h) + aoff + m * 2048 + k * 1024); } while (0)
; #define PG8_LDB(dst, b, h) do { _Pragma("unroll") for (int n = 0; n < 2; ++n) _Pragma("unroll") for (int k = 0; k < 2; ++k) dst[n][k] = *(const LAS bf16x8*)(lds + PG8_SB(b, h) + boff + n * 2048 + k * 1024); } while (0)
; #define PG8_MMA(ai, bj, At, Bt) do { __builtin_amdgcn_s_setprio(1); _Pragma("unroll") for (int m = 0; m < 4; ++m) _Pragma("unroll") for (int n = 0; n < 2; ++n) _Pragma("unroll") for (int k = 0; k < 2; ++k) \
;         acc[ai][bj][m][n] = __builtin_amdgcn_mfma_f32_16x16x32_bf16(Bt[n][k], At[m][k], acc[ai][bj][m][n], 0, 0, 0); __builtin_amdgcn_s_setprio(0); } while (0)
; #define PG8_WAIT_V(n) asm volatile("s_waitcnt vmcnt(" #n ")" ::: "memory")
; #define PG8_WAIT_L(n) asm volatile("s_waitcnt lgkmcnt(" #n ")" ::: "memory")
; #define PG8_BAR __builtin_amdgcn_s_barrier()
; #define PG8_SCHED __builtin_amdgcn_sched_barrier(0)
; template <class Epi, class Sched, bool ALIGN_EPI = false, bool SP2 = false>
; __device__ __forceinline__ void gemm_phase(LAS unsigned char* lds, const Gemm g, const Sched& S, const Epi& E) {
;     ...
;             PG8_LDB(B0, 0, 0); PG8_LDB(B1, 0, 1); PG8_SCHED; PG8_LDA(At, 0, 0); PG8_STAGE(PG8_SA(1, 1), a1 + hstep, voffA);
;             PG8_WAIT_V(8); PG8_WAIT_L(0); PG8_BAR; PG8_MMA(0, 0, At, B0); PG8_MMA(0, 1, At, B1); PG8_BAR; PG8_SCHED;
;             PG8_LDA(At, 0, 1); PG8_STAGE(PG8_SB(0, 0), b2, voffB); PG8_STAGE(PG8_SB(0, 1), b2 + hstep, voffB); PG8_STAGE(PG8_SA(0, 0), a2, voffA);
;             PG8_WAIT_V(8); PG8_WAIT_L(0); PG8_BAR; PG8_MMA(1, 0, At, B0); PG8_MMA(1, 1, At, B1); PG8_BAR; PG8_SCHED;
.LBB0_241:
	s_add_u32 s28, s14, 0xfff80080
	s_addc_u32 s29, s15, -1
	s_add_i32 s54, 0, 0x10000
	s_cmp_eq_u32 s62, 28
	s_cselect_b32 s31, s7, s29
	s_cselect_b32 s30, s49, s28
	s_cselect_b32 s29, s5, s65
	s_cselect_b32 s28, s50, s51
	s_add_i32 s68, 0, 0x14000
	v_add_u32_e32 v156, s54, v149
	v_add_u32_e32 v172, s68, v149
	ds_read_b128 v[140:143], v156
	ds_read_b128 v[144:147], v156 offset:1024
	ds_read_b128 v[152:155], v156 offset:2048
	ds_read_b128 v[156:159], v156 offset:3072
	ds_read_b128 v[160:163], v172
	ds_read_b128 v[164:167], v172 offset:1024
	ds_read_b128 v[168:171], v172 offset:2048
	ds_read_b128 v[172:175], v172 offset:3072
	v_lshl_add_u64 v[176:177], s[14:15], 0, v[138:139]
	s_add_i32 m0, s36, 0xc000
	ds_read_b128 v[186:189], v151
	ds_read_b128 v[190:193], v151 offset:1024
	ds_read_b128 v[194:197], v151 offset:2048
	ds_read_b128 v[198:201], v151 offset:3072
	ds_read_b128 v[202:205], v151 offset:4096
	ds_read_b128 v[222:225], v151 offset:5120
	ds_read_b128 v[226:229], v151 offset:6144
	ds_read_b128 v[230:233], v151 offset:7168
	global_load_lds_dwordx4 v[176:177], off
	v_lshl_add_u64 v[176:177], s[14:15], 0, v[136:137]
	s_add_i32 m0, s36, 0xe000
	s_nop 0
	global_load_lds_dwordx4 v[176:177], off
	s_waitcnt vmcnt(8)
	s_waitcnt lgkmcnt(0)
	s_barrier
	s_setprio 1
	s_waitcnt lgkmcnt(0)
	v_mfma_f32_16x16x32_bf16 v[126:129], v[140:143], v[186:189], v[126:129]
	v_mfma_f32_16x16x32_bf16 v[122:125], v[152:155], v[186:189], v[122:125]
	v_mfma_f32_16x16x32_bf16 v[110:113], v[140:143], v[194:197], v[110:113]
	v_mfma_f32_16x16x32_bf16 v[106:109], v[152:155], v[194:197], v[106:109]
	v_mfma_f32_16x16x32_bf16 v[94:97], v[140:143], v[202:205], v[94:97]
	v_mfma_f32_16x16x32_bf16 v[90:93], v[152:155], v[202:205], v[90:93]
	v_mfma_f32_16x16x32_bf16 v[78:81], v[140:143], v[226:229], v[78:81]
	v_mfma_f32_16x16x32_bf16 v[74:77], v[152:155], v[226:229], v[74:77]
	v_mfma_f32_16x16x32_bf16 v[126:129], v[144:147], v[190:193], v[126:129]
	v_mfma_f32_16x16x32_bf16 v[122:125], v[156:159], v[190:193], v[122:125]
	v_mfma_f32_16x16x32_bf16 v[110:113], v[144:147], v[198:201], v[110:113]
	v_mfma_f32_16x16x32_bf16 v[106:109], v[156:159], v[198:201], v[106:109]
	v_mfma_f32_16x16x32_bf16 v[94:97], v[144:147], v[222:225], v[94:97]
	v_mfma_f32_16x16x32_bf16 v[90:93], v[156:159], v[222:225], v[90:93]
	v_mfma_f32_16x16x32_bf16 v[78:81], v[144:147], v[230:233], v[78:81]
	v_mfma_f32_16x16x32_bf16 v[74:77], v[156:159], v[230:233], v[74:77]
	v_mfma_f32_16x16x32_bf16 v[118:121], v[160:163], v[186:189], v[118:121]
	v_mfma_f32_16x16x32_bf16 v[114:117], v[168:171], v[186:189], v[114:117]
	v_mfma_f32_16x16x32_bf16 v[102:105], v[160:163], v[194:197], v[102:105]
	v_mfma_f32_16x16x32_bf16 v[98:101], v[168:171], v[194:197], v[98:101]
	v_mfma_f32_16x16x32_bf16 v[86:89], v[160:163], v[202:205], v[86:89]
	v_mfma_f32_16x16x32_bf16 v[82:85], v[168:171], v[202:205], v[82:85]
	v_mfma_f32_16x16x32_bf16 v[70:73], v[160:163], v[226:229], v[70:73]
	v_mfma_f32_16x16x32_bf16 v[66:69], v[168:171], v[226:229], v[66:69]
	v_mfma_f32_16x16x32_bf16 v[118:121], v[164:167], v[190:193], v[118:121]
	v_mfma_f32_16x16x32_bf16 v[114:117], v[172:175], v[190:193], v[114:117]
	v_mfma_f32_16x16x32_bf16 v[102:105], v[164:167], v[198:201], v[102:105]
	v_mfma_f32_16x16x32_bf16 v[98:101], v[172:175], v[198:201], v[98:101]
	v_mfma_f32_16x16x32_bf16 v[86:89], v[164:167], v[222:225], v[86:89]
	v_mfma_f32_16x16x32_bf16 v[82:85], v[172:175], v[222:225], v[82:85]
	v_mfma_f32_16x16x32_bf16 v[70:73], v[164:167], v[230:233], v[70:73]
	v_mfma_f32_16x16x32_bf16 v[66:69], v[172:175], v[230:233], v[66:69]
	s_setprio 0
	s_barrier
	s_add_i32 s54, s54, s24
	v_lshl_add_u64 v[176:177], s[28:29], 0, v[0:1]
	s_mov_b32 m0, s54
	ds_read_b128 v[186:189], v151 offset:16384
	ds_read_b128 v[190:193], v151 offset:17408
	ds_read_b128 v[194:197], v151 offset:18432
	ds_read_b128 v[198:201], v151 offset:19456
	ds_read_b128 v[202:205], v151 offset:20480
	ds_read_b128 v[222:225], v151 offset:21504
	ds_read_b128 v[226:229], v151 offset:22528
	ds_read_b128 v[230:233], v151 offset:23552
	global_load_lds_dwordx4 v[176:177], off
	s_add_i32 m0, s54, 0x2000
	s_add_u32 s66, s28, 0x80000
	v_lshl_add_u64 v[234:235], s[28:29], 0, v[130:131]
	s_addc_u32 s67, s29, 0
	s_add_i32 s54, s68, s24
	global_load_lds_dwordx4 v[234:235], off
	v_lshl_add_u64 v[236:237], s[66:67], 0, v[0:1]
	s_mov_b32 m0, s54
	v_lshl_add_u64 v[238:239], s[30:31], 0, v[132:133]
	global_load_lds_dwordx4 v[236:237], off
	v_lshl_add_u64 v[236:237], s[66:67], 0, v[130:131]
	s_add_i32 m0, s54, 0x2000
	s_nop 0
	global_load_lds_dwordx4 v[236:237], off
	v_lshl_add_u64 v[236:237], s[30:31], 0, v[134:135]
	s_mov_b32 m0, s36
	s_nop 0
	global_load_lds_dwordx4 v[236:237], off
	s_mov_b32 m0, s37
	s_nop 0
	global_load_lds_dwordx4 v[238:239], off
	s_waitcnt vmcnt(8)
	s_waitcnt lgkmcnt(0)
	s_barrier
; #define PG8_STAGE(bufoff, gbase, voff) do { _Pragma("unroll") for (int _i = 0; _i < 2; ++_i) \
;         __builtin_amdgcn_global_load_lds((const unsigned*)((const char*)(gbase) + (voff)[_i]), (LAS unsigned*)(lds + (bufoff) + ldsw + _i * 8192), 16, 0, 0); } while (0)
; #define PG8_LDA(dst, b, h) do { _Pragma("unroll") for (int m = 0; m < 4; ++m) _Pragma("unroll") for (int k = 0; k < 2; ++k) dst[m][k] = *(const LAS bf16x8*)(lds + PG8_SA(b, h) + aoff + m * 2048 + k * 1024); } while (0)
; #define PG8_LDB(dst, b, h) do { _Pragma("unroll") for (int n = 0; n < 2; ++n) _Pragma("unroll") for (int k = 0; k < 2; ++k) dst[n][k] = *(const LAS bf16x8*)(lds + PG8_SB(b, h) + boff + n * 2048 + k * 1024); } while (0)
; #define PG8_MMA(ai, bj, At, Bt) do { __builtin_amdgcn_s_setprio(1); _Pragma("unroll") for (int m = 0; m < 4; ++m) _Pragma("unroll") for (int n = 0; n < 2; ++n) _Pragma("unroll") for (int k = 0; k < 2; ++k) \
;         acc[ai][bj][m][n] = __builtin_amdgcn_mfma_f32_16x16x32_bf16(Bt[n][k], At[m][k], acc[ai][bj][m][n], 0, 0, 0); __builtin_amdgcn_s_setprio(0); } while (0)
; #define PG8_WAIT_V(n) asm volatile("s_waitcnt vmcnt(" #n ")" ::: "memory")
; #define PG8_WAIT_L(n) asm volatile("s_waitcnt lgkmcnt(" #n ")" ::: "memory")
; #define PG8_BAR __builtin_amdgcn_s_barrier()
; #define PG8_SCHED __builtin_amdgcn_sched_barrier(0)
; template <class Epi, class Sched, bool ALIGN_EPI = false, bool SP2 = false>
; __device__ __forceinline__ void gemm_phase(LAS unsigned char* lds, const Gemm g, const Sched& S, const Epi& E) {
;     ...
;             PG8_WAIT_V(8); PG8_WAIT_L(0); PG8_BAR; PG8_MMA(1, 0, At, B0); PG8_MMA(1, 1, At, B1); PG8_BAR; PG8_SCHED;
;             PG8_LDB(B0, 1, 0); PG8_LDB(B1, 1, 1); PG8_SCHED; PG8_LDA(At, 1, 0); PG8_STAGE(PG8_SA(0, 1), a2 + hstep, voffA);
;             PG8_WAIT_V(8); PG8_WAIT_L(0); PG8_BAR; PG8_MMA(0, 0, At, B0); PG8_MMA(0, 1, At, B1); PG8_BAR; PG8_SCHED;
	s_setprio 1
	s_waitcnt lgkmcnt(0)
	v_mfma_f32_16x16x32_bf16 v[62:65], v[140:143], v[186:189], v[62:65]
	v_mfma_f32_16x16x32_bf16 v[58:61], v[152:155], v[186:189], v[58:61]
	v_mfma_f32_16x16x32_bf16 v[46:49], v[140:143], v[194:197], v[46:49]
	v_mfma_f32_16x16x32_bf16 v[42:45], v[152:155], v[194:197], v[42:45]
	v_mfma_f32_16x16x32_bf16 v[30:33], v[140:143], v[202:205], v[30:33]
	v_mfma_f32_16x16x32_bf16 v[26:29], v[152:155], v[202:205], v[26:29]
	v_mfma_f32_16x16x32_bf16 v[14:17], v[140:143], v[226:229], v[14:17]
	v_mfma_f32_16x16x32_bf16 v[10:13], v[152:155], v[226:229], v[10:13]
	v_mfma_f32_16x16x32_bf16 v[62:65], v[144:147], v[190:193], v[62:65]
	v_mfma_f32_16x16x32_bf16 v[58:61], v[156:159], v[190:193], v[58:61]
	v_mfma_f32_16x16x32_bf16 v[46:49], v[144:147], v[198:201], v[46:49]
	v_mfma_f32_16x16x32_bf16 v[42:45], v[156:159], v[198:201], v[42:45]
	v_mfma_f32_16x16x32_bf16 v[30:33], v[144:147], v[222:225], v[30:33]
	v_mfma_f32_16x16x32_bf16 v[26:29], v[156:159], v[222:225], v[26:29]
	v_mfma_f32_16x16x32_bf16 v[14:17], v[144:147], v[230:233], v[14:17]
	v_mfma_f32_16x16x32_bf16 v[10:13], v[156:159], v[230:233], v[10:13]
	v_mfma_f32_16x16x32_bf16 v[54:57], v[160:163], v[186:189], v[54:57]
	v_mfma_f32_16x16x32_bf16 v[50:53], v[168:171], v[186:189], v[50:53]
	v_mfma_f32_16x16x32_bf16 v[38:41], v[160:163], v[194:197], v[38:41]
	v_mfma_f32_16x16x32_bf16 v[34:37], v[168:171], v[194:197], v[34:37]
	v_mfma_f32_16x16x32_bf16 v[22:25], v[160:163], v[202:205], v[22:25]
	v_mfma_f32_16x16x32_bf16 v[18:21], v[168:171], v[202:205], v[18:21]
	v_mfma_f32_16x16x32_bf16 v[6:9], v[160:163], v[226:229], v[6:9]
	v_mfma_f32_16x16x32_bf16 v[2:5], v[168:171], v[226:229], v[2:5]
	v_mfma_f32_16x16x32_bf16 v[54:57], v[164:167], v[190:193], v[54:57]
	v_mfma_f32_16x16x32_bf16 v[50:53], v[172:175], v[190:193], v[50:53]
	v_mfma_f32_16x16x32_bf16 v[38:41], v[164:167], v[198:201], v[38:41]
	v_mfma_f32_16x16x32_bf16 v[34:37], v[172:175], v[198:201], v[34:37]
	v_mfma_f32_16x16x32_bf16 v[22:25], v[164:167], v[222:225], v[22:25]
	v_mfma_f32_16x16x32_bf16 v[18:21], v[172:175], v[222:225], v[18:21]
	v_mfma_f32_16x16x32_bf16 v[6:9], v[164:167], v[230:233], v[6:9]
	v_mfma_f32_16x16x32_bf16 v[2:5], v[172:175], v[230:233], v[2:5]
	s_setprio 0
	s_barrier
	s_add_i32 s54, 0, 0x18000
	s_add_i32 s66, 0, 0x1c000
	v_add_u32_e32 v156, s54, v149
	v_add_u32_e32 v172, s66, v149
	ds_read_b128 v[140:143], v156
	ds_read_b128 v[144:147], v156 offset:1024
	ds_read_b128 v[152:155], v156 offset:2048
	ds_read_b128 v[156:159], v156 offset:3072
	ds_read_b128 v[160:163], v172
	ds_read_b128 v[164:167], v172 offset:1024
	ds_read_b128 v[168:171], v172 offset:2048
	ds_read_b128 v[172:175], v172 offset:3072
	s_add_u32 s30, s30, 0x80000
	s_addc_u32 s31, s31, 0
	s_mov_b32 m0, s40
	v_lshl_add_u64 v[240:241], s[30:31], 0, v[134:135]
	ds_read_b128 v[186:189], v151 offset:32768
	ds_read_b128 v[190:193], v151 offset:33792
	ds_read_b128 v[194:197], v151 offset:34816
	ds_read_b128 v[198:201], v151 offset:35840
	ds_read_b128 v[202:205], v151 offset:36864
	ds_read_b128 v[222:225], v151 offset:37888
	ds_read_b128 v[226:229], v151 offset:38912
	ds_read_b128 v[230:233], v151 offset:39936
	global_load_lds_dwordx4 v[240:241], off
	v_lshl_add_u64 v[240:241], s[30:31], 0, v[132:133]
	s_mov_b32 m0, s41
	s_nop 0
	global_load_lds_dwordx4 v[240:241], off
	s_waitcnt vmcnt(8)
	s_waitcnt lgkmcnt(0)
	s_barrier
	s_setprio 1
	s_waitcnt lgkmcnt(0)
	v_mfma_f32_16x16x32_bf16 v[126:129], v[140:143], v[186:189], v[126:129]
	v_mfma_f32_16x16x32_bf16 v[122:125], v[152:155], v[186:189], v[122:125]
	v_mfma_f32_16x16x32_bf16 v[110:113], v[140:143], v[194:197], v[110:113]
	v_mfma_f32_16x16x32_bf16 v[106:109], v[152:155], v[194:197], v[106:109]
	v_mfma_f32_16x16x32_bf16 v[94:97], v[140:143], v[202:205], v[94:97]
	v_mfma_f32_16x16x32_bf16 v[90:93], v[152:155], v[202:205], v[90:93]
	v_mfma_f32_16x16x32_bf16 v[78:81], v[140:143], v[226:229], v[78:81]
	v_mfma_f32_16x16x32_bf16 v[74:77], v[152:155], v[226:229], v[74:77]
	v_mfma_f32_16x16x32_bf16 v[126:129], v[144:147], v[190:193], v[126:129]
	v_mfma_f32_16x16x32_bf16 v[122:125], v[156:159], v[190:193], v[122:125]
	v_mfma_f32_16x16x32_bf16 v[110:113], v[144:147], v[198:201], v[110:113]
	v_mfma_f32_16x16x32_bf16 v[106:109], v[156:159], v[198:201], v[106:109]
	v_mfma_f32_16x16x32_bf16 v[94:97], v[144:147], v[222:225], v[94:97]
	v_mfma_f32_16x16x32_bf16 v[90:93], v[156:159], v[222:225], v[90:93]
	v_mfma_f32_16x16x32_bf16 v[78:81], v[144:147], v[230:233], v[78:81]
	v_mfma_f32_16x16x32_bf16 v[74:77], v[156:159], v[230:233], v[74:77]
	v_mfma_f32_16x16x32_bf16 v[118:121], v[160:163], v[186:189], v[118:121]
	v_mfma_f32_16x16x32_bf16 v[114:117], v[168:171], v[186:189], v[114:117]
	v_mfma_f32_16x16x32_bf16 v[102:105], v[160:163], v[194:197], v[102:105]
	v_mfma_f32_16x16x32_bf16 v[98:101], v[168:171], v[194:197], v[98:101]
	v_mfma_f32_16x16x32_bf16 v[86:89], v[160:163], v[202:205], v[86:89]
	v_mfma_f32_16x16x32_bf16 v[82:85], v[168:171], v[202:205], v[82:85]
	v_mfma_f32_16x16x32_bf16 v[70:73], v[160:163], v[226:229], v[70:73]
	v_mfma_f32_16x16x32_bf16 v[66:69], v[168:171], v[226:229], v[66:69]
	v_mfma_f32_16x16x32_bf16 v[118:121], v[164:167], v[190:193], v[118:121]
	v_mfma_f32_16x16x32_bf16 v[114:117], v[172:175], v[190:193], v[114:117]
	v_mfma_f32_16x16x32_bf16 v[102:105], v[164:167], v[198:201], v[102:105]
	v_mfma_f32_16x16x32_bf16 v[98:101], v[172:175], v[198:201], v[98:101]
	v_mfma_f32_16x16x32_bf16 v[86:89], v[164:167], v[222:225], v[86:89]
	v_mfma_f32_16x16x32_bf16 v[82:85], v[172:175], v[222:225], v[82:85]
	v_mfma_f32_16x16x32_bf16 v[70:73], v[164:167], v[230:233], v[70:73]
	v_mfma_f32_16x16x32_bf16 v[66:69], v[172:175], v[230:233], v[66:69]
	s_setprio 0
	s_barrier
; #define PG8_STAGE(bufoff, gbase, voff) do { _Pragma("unroll") for (int _i = 0; _i < 2; ++_i) \
;         __builtin_amdgcn_global_load_lds((const unsigned*)((const char*)(gbase) + (voff)[_i]), (LAS unsigned*)(lds + (bufoff) + ldsw + _i * 8192), 16, 0, 0); } while (0)
; #define PG8_LDA(dst, b, h) do { _Pragma("unroll") for (int m = 0; m < 4; ++m) _Pragma("unroll") for (int k = 0; k < 2; ++k) dst[m][k] = *(const LAS bf16x8*)(lds + PG8_SA(b, h) + aoff + m * 2048 + k * 1024); } while (0)
; #define PG8_MMA(ai, bj, At, Bt) do { __builtin_amdgcn_s_setprio(1); _Pragma("unroll") for (int m = 0; m < 4; ++m) _Pragma("unroll") for (int n = 0; n < 2; ++n) _Pragma("unroll") for (int k = 0; k < 2; ++k) \
;         acc[ai][bj][m][n] = __builtin_amdgcn_mfma_f32_16x16x32_bf16(Bt[n][k], At[m][k], acc[ai][bj][m][n], 0, 0, 0); __builtin_amdgcn_s_setprio(0); } while (0)
; #define PG8_WAIT_V(n) asm volatile("s_waitcnt vmcnt(" #n ")" ::: "memory")
; #define PG8_WAIT_L(n) asm volatile("s_waitcnt lgkmcnt(" #n ")" ::: "memory")
; #define PG8_BAR __builtin_amdgcn_s_barrier()
; #define PG8_SCHED __builtin_amdgcn_sched_barrier(0)
; template <class Epi, class Sched, bool ALIGN_EPI = false, bool SP2 = false>
; __device__ __forceinline__ void gemm_phase(LAS unsigned char* lds, const Gemm g, const Sched& S, const Epi& E) {
;     ...
;             PG8_LDA(At, 1, 1); PG8_STAGE(PG8_SB(1, 0), b3, voffB); PG8_STAGE(PG8_SB(1, 1), b3 + hstep, voffB); PG8_STAGE(PG8_SA(1, 0), a3, voffA);
;             PG8_WAIT_V(8); PG8_WAIT_L(0); PG8_BAR; PG8_MMA(1, 0, At, B0); PG8_MMA(1, 1, At, B1); PG8_BAR; PG8_SCHED;
;     ...
;         if constexpr (ALIGN_EPI) { if (wr == 0) PG8_BAR; }
	s_add_i32 s30, s54, s24
	v_lshl_add_u64 v[176:177], v[176:177], 0, s[26:27]
	s_mov_b32 m0, s30
	ds_read_b128 v[186:189], v151 offset:49152
	ds_read_b128 v[190:193], v151 offset:50176
	ds_read_b128 v[194:197], v151 offset:51200
	ds_read_b128 v[198:201], v151 offset:52224
	ds_read_b128 v[202:205], v151 offset:53248
	ds_read_b128 v[222:225], v151 offset:54272
	ds_read_b128 v[226:229], v151 offset:55296
	ds_read_b128 v[230:233], v151 offset:56320
	global_load_lds_dwordx4 v[176:177], off
	s_add_i32 m0, s30, 0x2000
	s_add_u32 s28, s28, 0x80080
	v_lshl_add_u64 v[176:177], v[234:235], 0, s[26:27]
	s_addc_u32 s29, s29, 0
	s_add_i32 s30, s66, s24
	global_load_lds_dwordx4 v[176:177], off
	v_lshl_add_u64 v[176:177], s[28:29], 0, v[0:1]
	s_mov_b32 m0, s30
	s_nop 0
	global_load_lds_dwordx4 v[176:177], off
	v_lshl_add_u64 v[176:177], s[28:29], 0, v[130:131]
	s_add_i32 m0, s30, 0x2000
	s_nop 0
	global_load_lds_dwordx4 v[176:177], off
	v_lshl_add_u64 v[176:177], v[236:237], 0, s[26:27]
	s_mov_b32 m0, s42
	s_nop 0
	global_load_lds_dwordx4 v[176:177], off
	v_lshl_add_u64 v[176:177], v[238:239], 0, s[26:27]
	s_mov_b32 m0, s43
	s_nop 0
	global_load_lds_dwordx4 v[176:177], off
	s_waitcnt vmcnt(8)
	s_waitcnt lgkmcnt(0)
	s_barrier
	s_setprio 1
	s_waitcnt lgkmcnt(0)
	v_mfma_f32_16x16x32_bf16 v[62:65], v[140:143], v[186:189], v[62:65]
	v_mfma_f32_16x16x32_bf16 v[58:61], v[152:155], v[186:189], v[58:61]
	v_mfma_f32_16x16x32_bf16 v[46:49], v[140:143], v[194:197], v[46:49]
	v_mfma_f32_16x16x32_bf16 v[42:45], v[152:155], v[194:197], v[42:45]
	v_mfma_f32_16x16x32_bf16 v[30:33], v[140:143], v[202:205], v[30:33]
	v_mfma_f32_16x16x32_bf16 v[26:29], v[152:155], v[202:205], v[26:29]
	v_mfma_f32_16x16x32_bf16 v[14:17], v[140:143], v[226:229], v[14:17]
	v_mfma_f32_16x16x32_bf16 v[10:13], v[152:155], v[226:229], v[10:13]
	v_mfma_f32_16x16x32_bf16 v[62:65], v[144:147], v[190:193], v[62:65]
	v_mfma_f32_16x16x32_bf16 v[58:61], v[156:159], v[190:193], v[58:61]
	v_mfma_f32_16x16x32_bf16 v[46:49], v[144:147], v[198:201], v[46:49]
	v_mfma_f32_16x16x32_bf16 v[42:45], v[156:159], v[198:201], v[42:45]
	v_mfma_f32_16x16x32_bf16 v[30:33], v[144:147], v[222:225], v[30:33]
	v_mfma_f32_16x16x32_bf16 v[26:29], v[156:159], v[222:225], v[26:29]
	v_mfma_f32_16x16x32_bf16 v[14:17], v[144:147], v[230:233], v[14:17]
	v_mfma_f32_16x16x32_bf16 v[10:13], v[156:159], v[230:233], v[10:13]
	v_mfma_f32_16x16x32_bf16 v[54:57], v[160:163], v[186:189], v[54:57]
	v_mfma_f32_16x16x32_bf16 v[50:53], v[168:171], v[186:189], v[50:53]
	v_mfma_f32_16x16x32_bf16 v[38:41], v[160:163], v[194:197], v[38:41]
	v_mfma_f32_16x16x32_bf16 v[34:37], v[168:171], v[194:197], v[34:37]
	v_mfma_f32_16x16x32_bf16 v[22:25], v[160:163], v[202:205], v[22:25]
	v_mfma_f32_16x16x32_bf16 v[18:21], v[168:171], v[202:205], v[18:21]
	v_mfma_f32_16x16x32_bf16 v[6:9], v[160:163], v[226:229], v[6:9]
	v_mfma_f32_16x16x32_bf16 v[2:5], v[168:171], v[226:229], v[2:5]
	v_mfma_f32_16x16x32_bf16 v[54:57], v[164:167], v[190:193], v[54:57]
	v_mfma_f32_16x16x32_bf16 v[50:53], v[172:175], v[190:193], v[50:53]
	v_mfma_f32_16x16x32_bf16 v[38:41], v[164:167], v[198:201], v[38:41]
	v_mfma_f32_16x16x32_bf16 v[34:37], v[172:175], v[198:201], v[34:37]
	v_mfma_f32_16x16x32_bf16 v[22:25], v[164:167], v[222:225], v[22:25]
	v_mfma_f32_16x16x32_bf16 v[18:21], v[172:175], v[222:225], v[18:21]
	v_mfma_f32_16x16x32_bf16 v[6:9], v[164:167], v[230:233], v[6:9]
	v_mfma_f32_16x16x32_bf16 v[2:5], v[172:175], v[230:233], v[2:5]
	s_setprio 0
	s_barrier
	s_add_i32 s62, s62, 2
	s_add_u32 s51, s51, 0x100
	s_addc_u32 s65, s65, 0
	s_add_u32 s14, s14, 0x100
	s_addc_u32 s15, s15, 0
	s_cmp_gt_u32 s62, 29
	s_cbranch_scc0 .LBB0_241
	s_and_b64 vcc, exec, s[2:3]
	s_cbranch_vccz .LBB0_244
	s_barrier
